# runtime check that every workgroup shares its XCC with workgroup c%8 (else all seams fall back to the full grid barrier)
# baseline (speedup 1.0000x reference)
.LBB0_5:
	s_or_b64 exec, exec, s[4:5]
	s_load_dwordx2 s[4:5], s[56:57], 0x80
	s_getreg_b32 s6, hwreg(HW_REG_XCC_ID, 0, 4)
	s_add_i32 s6, s6, 1
	s_lshl_b32 s7, s45, 2
	s_add_u32 s7, s7, 0x1d403800
	v_mov_b32_e32 v1, s6
	v_mov_b32_e32 v2, 0
	s_waitcnt lgkmcnt(0)
	s_add_u32 s4, s4, s7
	s_addc_u32 s5, s5, 0
	global_store_dword v2, v1, s[4:5]
	s_add_u32 s80, s56, 0x90
	s_addc_u32 s81, s57, 0
	s_ashr_i32 s3, s45, 31
	s_lshr_b32 s1, s3, 29
	s_add_i32 s1, s45, s1
	s_ashr_i32 s7, s1, 3
	s_and_b32 s1, s1, -8
	s_sub_i32 s8, s45, s1
	s_cmpk_lt_i32 s45, 0xb00
	s_cselect_b64 s[4:5], -1, 0
	v_lshrrev_b32_e32 v1, 20, v0
	v_lshrrev_b32_e32 v0, 10, v0
	v_writelane_b32 v254, s4, 2
	s_cmpk_lt_i32 s45, 0x500
	v_or_b32_e32 v0, v0, v1
	s_movk_i32 s1, 0x3ff
	v_writelane_b32 v254, s5, 3
	s_cselect_b64 s[4:5], -1, 0
	s_cmp_lt_i32 s8, 0
	v_and_or_b32 v0, v0, s1, v194
	s_movk_i32 s1, 0x161
	s_cselect_b32 s1, s1, 0x160
	s_mul_i32 s1, s8, s1
	s_movk_i32 s2, 0xa1
	v_writelane_b32 v254, s4, 4
	s_cselect_b32 s2, s2, 0xa0
	s_add_i32 s1, s1, s7
	v_writelane_b32 v254, s5, 5
	s_mul_hi_i32 s4, s1, 0x2e8ba2e9
	s_lshr_b32 s5, s4, 31
	s_ashr_i32 s4, s4, 5
	s_add_i32 s4, s4, s5
	s_mul_i32 s2, s8, s2
	s_lshl_b32 s5, s4, 3
	s_mulk_i32 s4, 0xb0
	s_add_i32 s2, s2, s7
	s_sub_i32 s6, 0x80, s5
	s_sub_i32 s1, s1, s4
	v_writelane_b32 v254, s8, 6
	s_mul_hi_i32 s4, s2, 0x66666667
	s_min_i32 s6, s6, 8
	v_writelane_b32 v254, s7, 7
	s_lshr_b32 s7, s4, 31
	s_ashr_i32 s4, s4, 5
	s_add_i32 s4, s4, s7
	s_abs_i32 s7, s6
	v_cvt_f32_u32_e32 v1, s7
	s_sub_i32 s11, 0, s7
	s_abs_i32 s10, s1
	s_lshl_b32 s8, s4, 3
	v_rcp_iflag_f32_e32 v1, v1
	s_mulk_i32 s4, 0x50
	s_sub_i32 s9, 0x80, s8
	s_sub_i32 s2, s2, s4
	v_mul_f32_e32 v1, 0x4f7ffffe, v1
	v_cvt_u32_f32_e32 v1, v1
	s_xor_b32 s4, s1, s6
	s_min_i32 s9, s9, 8
	s_ashr_i32 s4, s4, 31
	v_readfirstlane_b32 s12, v1
	s_mul_i32 s11, s11, s12
	s_mul_hi_u32 s11, s12, s11
	s_add_i32 s12, s12, s11
	s_mul_hi_u32 s11, s10, s12
	s_mul_i32 s12, s11, s7
	s_sub_i32 s10, s10, s12
	s_add_i32 s12, s11, 1
	s_sub_i32 s13, s10, s7
	s_cmp_ge_u32 s10, s7
	s_cselect_b32 s11, s12, s11
	s_cselect_b32 s10, s13, s10
	s_add_i32 s12, s11, 1
	s_cmp_ge_u32 s10, s7
	s_cselect_b32 s7, s12, s11
	s_xor_b32 s7, s7, s4
	s_sub_i32 s10, s7, s4
	s_mul_i32 s4, s10, s6
	s_sub_i32 s1, s1, s4
	s_abs_i32 s4, s9
	v_cvt_f32_u32_e32 v1, s4
	s_add_i32 s12, s5, s1
	s_mov_b32 s6, s12
	s_ashr_i32 s13, s12, 31
	v_rcp_iflag_f32_e32 v1, v1
	v_writelane_b32 v254, s6, 8
	s_ashr_i32 s11, s10, 31
	s_abs_i32 s5, s2
	v_writelane_b32 v254, s7, 9
	s_lshl_b64 s[6:7], s[12:13], 19
	v_writelane_b32 v254, s6, 10
	v_mul_f32_e32 v1, 0x4f7ffffe, v1
	v_cvt_u32_f32_e32 v1, v1
	v_writelane_b32 v254, s7, 11
	s_mov_b32 s6, s10
	v_writelane_b32 v254, s6, 12
	s_xor_b32 s1, s2, s9
	s_ashr_i32 s1, s1, 31
	v_writelane_b32 v254, s7, 13
	s_lshl_b64 s[6:7], s[10:11], 19
	v_writelane_b32 v254, s6, 14
	s_load_dword s0, s[56:57], 0x88
	v_mov_b32_e32 v99, 0
	v_writelane_b32 v254, s7, 15
	s_sub_i32 s6, 0, s4
	v_readfirstlane_b32 s7, v1
	s_mul_i32 s6, s6, s7
	s_mul_hi_u32 s6, s7, s6
	s_add_i32 s7, s7, s6
	s_mul_hi_u32 s6, s5, s7
	s_mul_i32 s7, s6, s4
	s_sub_i32 s5, s5, s7
	s_add_i32 s7, s6, 1
	s_sub_i32 s10, s5, s4
	s_cmp_ge_u32 s5, s4
	s_cselect_b32 s6, s7, s6
	s_cselect_b32 s5, s10, s5
	s_add_i32 s7, s6, 1
	s_cmp_ge_u32 s5, s4
	s_cselect_b32 s4, s7, s6
	s_xor_b32 s4, s4, s1
	s_sub_i32 s4, s4, s1
	s_mul_i32 s1, s4, s9
	s_sub_i32 s1, s2, s1
	s_add_i32 s6, s8, s1
	s_add_i32 s1, 0, 0x1d2e0
	v_writelane_b32 v254, s1, 16
	s_add_i32 s1, 0, 0x1d2d0
	v_writelane_b32 v254, s1, 17
	s_add_i32 s1, 0, 0x1d300
	v_writelane_b32 v254, s1, 18
	s_add_i32 s1, 0, 0x1d2f0
	v_writelane_b32 v254, s1, 19
	s_add_i32 s1, 0, 0x1d320
	v_writelane_b32 v254, s1, 20
	s_add_i32 s1, 0, 0x1d310
	v_writelane_b32 v254, s1, 21
	s_add_i32 s1, 0, 0x1d340
	v_writelane_b32 v254, s1, 22
	s_add_i32 s1, 0, 0x1d330
	v_writelane_b32 v254, s1, 23
	s_add_i32 s1, 0, 0x1d370
	v_writelane_b32 v254, s1, 24
	s_add_i32 s1, 0, 0x1d350
	v_writelane_b32 v254, s1, 25
	s_add_i32 s1, 0, 0x1d360
	v_writelane_b32 v254, s1, 26
	s_add_i32 s1, 0, 0x1d390
	v_writelane_b32 v254, s1, 27
	s_add_i32 s1, 0, 0x1d380
	v_writelane_b32 v254, s1, 28
	s_add_i32 s1, 0, 0x1d3b0
	v_writelane_b32 v254, s1, 29
	s_add_i32 s1, 0, 0x1d3a0
	v_writelane_b32 v254, s1, 30
	s_add_i32 s1, 0, 0x1d3d0
	v_writelane_b32 v254, s1, 31
	s_add_i32 s1, 0, 0x1d3c0
	v_writelane_b32 v254, s1, 32
	s_add_i32 s1, 0, 0x1d400
	v_writelane_b32 v254, s1, 33
	s_add_i32 s1, 0, 0x1d410
	v_writelane_b32 v254, s1, 34
	s_add_i32 s1, 0, 0x1d420
	v_writelane_b32 v254, s1, 35
	s_add_i32 s1, 0, 0x1d414
	v_writelane_b32 v254, s1, 36
	s_add_i32 s1, 0, 0x1d404
	v_writelane_b32 v254, s1, 37
	s_add_i32 s1, 0, 0x1d418
	v_writelane_b32 v254, s1, 38
	s_add_i32 s1, 0, 0x1d408
	v_writelane_b32 v254, s1, 39
	s_add_i32 s1, 0, 0x1d41c
	v_writelane_b32 v254, s1, 40
	s_add_i32 s1, 0, 0x1d40c
	v_writelane_b32 v254, s1, 41
	s_add_i32 s1, 0, 0x20400
	v_writelane_b32 v254, s1, 42
	s_add_i32 s1, 0, 0x20160
	v_writelane_b32 v254, s1, 43
	s_add_i32 s1, 0, 0x20164
	v_writelane_b32 v254, s1, 44
	v_cmp_eq_u32_e64 s[8:9], 0, v0
	s_mov_b32 s2, s6
	s_ashr_i32 s7, s6, 31
	v_writelane_b32 v254, s8, 45
	s_lshl_b64 s[6:7], s[6:7], 19
	s_ashr_i32 s5, s4, 31
	v_writelane_b32 v254, s9, 46
	v_writelane_b32 v254, s2, 47
	s_mov_b32 s29, 0xffff0000
	v_mbcnt_lo_u32_b32 v1, -1, 0
	v_writelane_b32 v254, s3, 48
	v_writelane_b32 v254, s6, 49
	s_mov_b32 s2, s4
	s_lshl_b64 s[4:5], s[4:5], 19
	v_writelane_b32 v254, s7, 50
	v_writelane_b32 v254, s2, 51
	v_mbcnt_hi_u32_b32 v202, -1, v1
	v_and_b32_e32 v203, 64, v202
	v_writelane_b32 v254, s3, 52
	v_writelane_b32 v254, s4, 53
	s_mov_b32 s31, 0x800000
	s_movk_i32 s98, 0x7fff
	v_writelane_b32 v254, s5, 54
	v_writelane_b32 v254, s56, 55
	s_movk_i32 s99, 0x1400
	s_mov_b32 s40, 0xbfb8aa3b
	v_writelane_b32 v254, s57, 56
	v_writelane_b32 v254, s80, 57
	s_mov_b32 s41, 0xffff
	v_mov_b32_e32 v195, 0x260
	v_mov_b32_e32 v196, 0x42180000
	v_mov_b32_e32 v197, 0x3ecc95a3
	v_mov_b32_e32 v198, 0x39500d01
	v_mov_b32_e32 v199, 0x358637bd
	v_mov_b32_e32 v200, 0x2000
	v_mov_b32_e32 v201, 1
	v_add_u32_e32 v204, 64, v203
	v_xor_b32_e32 v205, 1, v202
	v_xor_b32_e32 v206, 2, v202
	v_xor_b32_e32 v207, 4, v202
	v_xor_b32_e32 v208, 8, v202
	v_xor_b32_e32 v209, 16, v202
	v_xor_b32_e32 v210, 32, v202
	v_mov_b32_e32 v211, 0xff800000
	v_mov_b32_e32 v212, 0x200
	v_mov_b32_e32 v213, 0x50000
	v_mov_b32_e32 v214, 0x7f800000
	v_mov_b32_e32 v215, 0x7fc00000
	v_mov_b32_e32 v216, 0xffc
	v_mov_b64_e32 v[182:183], 0x4ff
	v_mov_b32_e32 v217, 0x3e38aa3b
	v_mov_b64_e32 v[184:185], 0x1ff
	v_mov_b64_e32 v[186:187], 0xaff
	s_mov_b32 s38, 0x41c00000
	s_mov_b32 s39, 0xb2a5705f
	s_mov_b32 s24, 0x42ce8ed0
	s_mov_b32 s25, 0xc2b17218
	s_mov_b32 s34, 0x7f800000
	s_mov_b32 s35, 0x3f2aaaab
	s_mov_b32 s36, 0x3f317218
	s_mov_b32 s37, 0x33800000
	s_movk_i32 s30, 0x1600
	s_movk_i32 s28, 0x2820
	s_mov_b32 s46, 0x3a800000
	s_mov_b64 s[48:49], 0x50000
	s_mov_b64 s[50:51], 0xa0000
	s_mov_b64 s[52:53], 0xf0000
	s_mov_b64 s[54:55], 0x1000
	s_mov_b64 s[58:59], 0x80
	s_mov_b64 s[60:61], 0x8000
	s_mov_b64 s[62:63], 0x14000
	v_writelane_b32 v254, s81, 58
	s_branch .LBB0_10

.LBB0_413:
	s_mov_b64 s[8:9], s[56:57]
	s_load_dword s1, s[8:9], 0x8c
	s_add_i32 s0, s91, 1
	s_mov_b64 s[6:7], -1
	s_waitcnt lgkmcnt(0)
	s_cmp_ge_i32 s0, s1
	s_cbranch_scc1 .LBB0_9
	s_cmp_eq_u32 s91, 0
	s_cbranch_scc1 .Lgb_full
	s_cmp_eq_u32 s91, 1
	s_cbranch_scc0 .Lchk_done
	s_load_dwordx2 s[4:5], s[56:57], 0x80
	v_and_b32_e32 v0, 63, v194
	v_lshlrev_b32_e32 v1, 2, v0
	v_and_b32_e32 v2, 7, v0
	v_lshlrev_b32_e32 v2, 2, v2
	s_waitcnt lgkmcnt(0)
	s_add_u32 s4, s4, 0x1d403800
	s_addc_u32 s5, s5, 0
	global_load_dword v3, v1, s[4:5] sc1
	global_load_dword v4, v1, s[4:5] offset:256 sc1
	global_load_dword v5, v1, s[4:5] offset:512 sc1
	global_load_dword v6, v1, s[4:5] offset:768 sc1
	global_load_dword v7, v2, s[4:5] sc1
	s_waitcnt vmcnt(0)
	v_xor_b32_e32 v3, v3, v7
	v_xor_b32_e32 v4, v4, v7
	v_xor_b32_e32 v5, v5, v7
	v_xor_b32_e32 v6, v6, v7
	v_or3_b32 v3, v3, v4, v5
	v_or_b32_e32 v3, v3, v6
	v_cmp_ne_u32_e32 vcc, 0, v3
	s_nop 1
	s_mov_b64 s[4:5], vcc
	v_cmp_eq_u32_e32 vcc, 0, v7
	s_nop 1
	s_or_b64 s[4:5], s[4:5], vcc
	s_cmp_eq_u64 s[4:5], 0
	s_cselect_b32 s4, 1, 0
	s_nop 0
	v_writelane_b32 v255, s4, 21
.Lchk_done:
	v_readlane_b32 s2, v255, 21
	s_nop 3
	s_cmp_eq_u32 s2, 0
	s_cbranch_scc1 .Lgb_full
	s_cmp_eq_u32 s91, 32
	s_cbranch_scc1 .Lgb_full
	s_add_i32 s1, s91, -1
	s_and_b32 s1, s1, 7
	s_movk_i32 s2, 0xe1
	s_bitcmp1_b32 s2, s1
	s_cbranch_scc1 .Lgb_start
	s_movk_i32 s2, 0xc
	s_bitcmp1_b32 s2, s1
	s_cbranch_scc1 .Lxb_start
